# context mixer phase: second-round items rotated past the scan blocks (heavy = nsc for every group)
# speedup vs baseline: 1.0040x; 1.0040x over previous
.LBB0_759:
	s_or_b64 exec, exec, s[0:1]
	s_lshl_b32 s24, s84, 3
	s_or_b32 s76, s24, 0x280
	v_readlane_b32 s0, v251, 0
	s_cmp_ge_i32 s0, s76
	s_waitcnt lgkmcnt(0)
	s_barrier
	s_cbranch_scc1 .LBB0_798
	v_readlane_b32 s0, v249, 15
	v_readlane_b32 s1, v249, 16
	s_and_b64 s[0:1], s[36:37], s[0:1]
	s_and_b64 s[0:1], s[0:1], exec
	s_mov_b32 s0, s24
	s_lshr_b32 s47, s85, 7
	v_cvt_f32_ubyte0_e32 v0, s47
	v_rcp_iflag_f32_e32 v0, v0
	s_lshr_b32 s13, s85, 4
	s_or_b32 s1, s24, 0x200
	v_writelane_b32 v248, s1, 23
	v_mul_f32_e32 v0, 0x4f7ffffe, v0
	v_cvt_u32_f32_e32 v0, v0
	v_readlane_b32 s1, v248, 21
	s_lshr_b32 s49, s1, 6
	v_readlane_b32 s1, v249, 23
	v_readfirstlane_b32 s12, v0
	v_cvt_f32_ubyte0_e32 v0, s13
	v_rcp_iflag_f32_e32 v0, v0
	s_sub_i32 s0, s1, s0
	s_sub_i32 s1, 0, s47
	s_mul_i32 s1, s1, s12
	v_mul_f32_e32 v0, 0x4f7ffffe, v0
	v_cvt_u32_f32_e32 v0, v0
	s_mul_hi_u32 s1, s12, s1
	s_add_i32 s1, s12, s1
	v_writelane_b32 v248, s1, 25
	s_sub_i32 s1, 0, s13
	v_readfirstlane_b32 s12, v0
	s_mul_i32 s1, s1, s12
	s_mul_hi_u32 s1, s12, s1
	v_writelane_b32 v248, s13, 20
	s_add_i32 s1, s12, s1
	v_writelane_b32 v248, s1, 27
	v_readlane_b32 s1, v249, 34
	s_mul_hi_u32 s1, s0, s1
	s_mul_i32 s1, s1, s94
	s_sub_i32 s0, s0, s1
	s_add_u32 s46, s85, -1
	s_lshl_b32 s45, s85, 3
	s_sub_i32 s1, s0, s94
	s_cmp_ge_u32 s0, s94
	s_cselect_b32 s0, s1, s0
	s_sub_i32 s1, s0, s94
	s_cmp_ge_u32 s0, s94
	s_cselect_b32 s0, s1, s0
	s_mov_b32 s44, 0
	v_writelane_b32 v248, s0, 24
	s_lshl_b32 s48, s51, 15
	s_add_i32 s0, s51, -1
	s_lshl_b32 s51, s85, 9
	v_readlane_b32 s25, v251, 0
	v_writelane_b32 v248, s0, 26
	s_branch .LBB0_764
